# v12 with non-temporal stores in the FFN-up epilogue (U is streamed out and read once one phase later)
# baseline (speedup 1.0000x reference)
.LBB0_452:
	s_waitcnt lgkmcnt(0)
	v_lshl_add_u32 v129, s87, 8, v221
	v_lshl_or_b32 v132, s33, 8, v222
	v_ashrrev_i32_e32 v131, 31, v129
	v_ashrrev_i32_e32 v133, 31, v132
	v_mul_lo_u32 v131, s14, v131
	v_mul_lo_u32 v135, s15, v129
	v_mad_u64_u32 v[146:147], s[2:3], s14, v129, 0
	v_lshl_add_u64 v[132:133], v[132:133], 1, s[30:31]
	v_add3_u32 v147, v147, v131, v135
	v_lshl_add_u64 v[150:151], v[146:147], 1, v[132:133]
	v_pk_mul_f32 v[146:147], v[126:127], v[144:145] op_sel_hi:[1,0]
	v_pk_mul_f32 v[152:153], v[122:123], v[144:145] op_sel_hi:[1,0]
	v_pk_mul_f32 v[148:149], v[124:125], v[144:145] op_sel_hi:[1,0]
	v_pk_mul_f32 v[154:155], v[120:121], v[144:145] op_sel_hi:[1,0]
	v_max_f32_e32 v143, 0, v146
	v_max_f32_e32 v146, 0, v147
	v_max_f32_e32 v147, 0, v153
	v_max_f32_e32 v135, 0, v148
	v_max_f32_e32 v137, 0, v154
	v_max_f32_e32 v139, 0, v149
	v_max_f32_e32 v141, 0, v155
	v_max_f32_e32 v145, 0, v152
	v_mul_f32_e32 v148, v146, v146
	v_mul_f32_e32 v149, v147, v147
	v_mul_f32_e32 v135, v135, v135
	v_mul_f32_e32 v137, v137, v137
	v_mul_f32_e32 v139, v139, v139
	v_mul_f32_e32 v141, v141, v141
	v_mul_f32_e32 v143, v143, v143
	v_mul_f32_e32 v145, v145, v145
	v_cvt_pk_bf16_f32 v146, v135, v139
	v_cvt_pk_bf16_f32 v147, v143, v148
	v_cvt_pk_bf16_f32 v148, v137, v141
	v_cvt_pk_bf16_f32 v149, v145, v149
	global_store_dwordx4 v[150:151], v[146:149], off nt
	v_pk_mul_f32 v[152:153], v[114:115], v[144:145] op_sel_hi:[1,0]
	s_nop 0
	v_pk_mul_f32 v[146:147], v[118:119], v[144:145] op_sel_hi:[1,0]
	v_pk_mul_f32 v[148:149], v[116:117], v[144:145] op_sel_hi:[1,0]
	v_pk_mul_f32 v[144:145], v[112:113], v[144:145] op_sel_hi:[1,0]
	v_max_f32_e32 v135, 0, v148
	v_max_f32_e32 v137, 0, v144
	v_max_f32_e32 v144, 0, v152
	v_mul_f32_e32 v135, v135, v135
	v_max_f32_e32 v139, 0, v149
	v_max_f32_e32 v141, 0, v145
	v_max_f32_e32 v143, 0, v146
	v_mul_f32_e32 v148, v144, v144
	v_max_f32_e32 v144, 0, v147
	v_max_f32_e32 v145, 0, v153
	v_mul_f32_e32 v137, v137, v137
	v_mul_f32_e32 v139, v139, v139
	v_mul_f32_e32 v143, v143, v143
	v_mul_f32_e32 v146, v144, v144
	v_mul_f32_e32 v147, v145, v145
	v_cvt_pk_bf16_f32 v144, v135, v139
	v_cvt_pk_bf16_f32 v145, v143, v146
	v_or_b32_e32 v135, 16, v129
	v_mul_f32_e32 v141, v141, v141
	v_cvt_pk_bf16_f32 v146, v137, v141
	v_cvt_pk_bf16_f32 v147, v148, v147
	global_store_dwordx4 v[150:151], v[144:147], off offset:256 nt
	v_mul_lo_u32 v137, s15, v135
	v_pk_mul_f32 v[150:151], v[106:107], v[142:143] op_sel_hi:[1,0]
	v_mad_u64_u32 v[144:145], s[2:3], s14, v135, 0
	v_add3_u32 v145, v145, v131, v137
	v_lshl_add_u64 v[148:149], v[144:145], 1, v[132:133]
	v_pk_mul_f32 v[144:145], v[110:111], v[142:143] op_sel_hi:[1,0]
	v_pk_mul_f32 v[146:147], v[108:109], v[142:143] op_sel_hi:[1,0]
	v_pk_mul_f32 v[152:153], v[104:105], v[142:143] op_sel_hi:[1,0]
	v_max_f32_e32 v143, 0, v144
	v_max_f32_e32 v144, 0, v150
	v_max_f32_e32 v139, 0, v147
	v_mul_f32_e32 v147, v144, v144
	v_max_f32_e32 v144, 0, v145
	v_max_f32_e32 v135, 0, v146
	v_max_f32_e32 v137, 0, v152
	v_max_f32_e32 v141, 0, v153
	v_max_f32_e32 v145, 0, v151
	v_mul_f32_e32 v146, v144, v144
	v_mul_f32_e32 v135, v135, v135
	v_mul_f32_e32 v137, v137, v137
	v_mul_f32_e32 v139, v139, v139
	v_mul_f32_e32 v141, v141, v141
	v_mul_f32_e32 v143, v143, v143
	v_mul_f32_e32 v150, v145, v145
	v_cvt_pk_bf16_f32 v144, v135, v139
	v_cvt_pk_bf16_f32 v145, v143, v146
	v_cvt_pk_bf16_f32 v146, v137, v141
	v_cvt_pk_bf16_f32 v147, v147, v150
	global_store_dwordx4 v[148:149], v[144:147], off nt
	v_pk_mul_f32 v[150:151], v[98:99], v[142:143] op_sel_hi:[1,0]
	s_nop 0
	v_pk_mul_f32 v[144:145], v[102:103], v[142:143] op_sel_hi:[1,0]
	v_pk_mul_f32 v[146:147], v[100:101], v[142:143] op_sel_hi:[1,0]
	v_pk_mul_f32 v[142:143], v[96:97], v[142:143] op_sel_hi:[1,0]
	v_max_f32_e32 v135, 0, v146
	v_max_f32_e32 v137, 0, v142
	v_max_f32_e32 v141, 0, v143
	v_max_f32_e32 v142, 0, v144
	v_max_f32_e32 v143, 0, v150
	v_mul_f32_e32 v135, v135, v135
	v_max_f32_e32 v139, 0, v147
	v_mul_f32_e32 v144, v142, v142
	v_mul_f32_e32 v146, v143, v143
	v_max_f32_e32 v142, 0, v145
	v_max_f32_e32 v143, 0, v151
	v_mul_f32_e32 v137, v137, v137
	v_mul_f32_e32 v139, v139, v139
	v_mul_f32_e32 v145, v142, v142
	v_mul_f32_e32 v147, v143, v143
	v_cvt_pk_bf16_f32 v142, v135, v139
	v_cvt_pk_bf16_f32 v143, v144, v145
	v_or_b32_e32 v135, 32, v129
	v_mul_f32_e32 v141, v141, v141
	v_cvt_pk_bf16_f32 v144, v137, v141
	v_cvt_pk_bf16_f32 v145, v146, v147
	global_store_dwordx4 v[148:149], v[142:145], off offset:256 nt
	v_mul_lo_u32 v137, s15, v135
	v_pk_mul_f32 v[148:149], v[90:91], v[140:141] op_sel_hi:[1,0]
	v_mad_u64_u32 v[142:143], s[2:3], s14, v135, 0
	v_add3_u32 v143, v143, v131, v137
	v_lshl_add_u64 v[146:147], v[142:143], 1, v[132:133]
	v_pk_mul_f32 v[142:143], v[94:95], v[140:141] op_sel_hi:[1,0]
	v_pk_mul_f32 v[144:145], v[92:93], v[140:141] op_sel_hi:[1,0]
	v_max_f32_e32 v142, 0, v142
	v_pk_mul_f32 v[150:151], v[88:89], v[140:141] op_sel_hi:[1,0]
	v_max_f32_e32 v135, 0, v144
	v_max_f32_e32 v139, 0, v145
	v_max_f32_e32 v144, 0, v148
	v_mul_f32_e32 v145, v142, v142
	v_max_f32_e32 v142, 0, v143
	v_max_f32_e32 v137, 0, v150
	v_max_f32_e32 v141, 0, v151
	v_mul_f32_e32 v148, v144, v144
	v_max_f32_e32 v143, 0, v149
	v_mul_f32_e32 v144, v142, v142
	v_mul_f32_e32 v135, v135, v135
	v_mul_f32_e32 v137, v137, v137
	v_mul_f32_e32 v139, v139, v139
	v_mul_f32_e32 v141, v141, v141
	v_mul_f32_e32 v149, v143, v143
	v_cvt_pk_bf16_f32 v142, v135, v139
	v_cvt_pk_bf16_f32 v143, v145, v144
	v_cvt_pk_bf16_f32 v144, v137, v141
	v_cvt_pk_bf16_f32 v145, v148, v149
	global_store_dwordx4 v[146:147], v[142:145], off nt
	v_pk_mul_f32 v[148:149], v[82:83], v[140:141] op_sel_hi:[1,0]
	s_nop 0
	v_pk_mul_f32 v[142:143], v[86:87], v[140:141] op_sel_hi:[1,0]
	v_pk_mul_f32 v[144:145], v[84:85], v[140:141] op_sel_hi:[1,0]
	v_pk_mul_f32 v[140:141], v[80:81], v[140:141] op_sel_hi:[1,0]
	v_max_f32_e32 v135, 0, v144
	v_max_f32_e32 v137, 0, v140
	v_max_f32_e32 v140, 0, v141
	v_mul_f32_e32 v144, v140, v140
	v_max_f32_e32 v140, 0, v142
	v_max_f32_e32 v141, 0, v148
	v_mul_f32_e32 v135, v135, v135
	v_max_f32_e32 v139, 0, v145
	v_mul_f32_e32 v142, v140, v140
	v_mul_f32_e32 v145, v141, v141
	v_max_f32_e32 v140, 0, v143
	v_max_f32_e32 v141, 0, v149
	v_mul_f32_e32 v137, v137, v137
	v_mul_f32_e32 v139, v139, v139
	v_mul_f32_e32 v143, v140, v140
	v_mul_f32_e32 v148, v141, v141
	v_cvt_pk_bf16_f32 v140, v135, v139
	v_cvt_pk_bf16_f32 v141, v142, v143
	v_or_b32_e32 v135, 48, v129
	v_cvt_pk_bf16_f32 v142, v137, v144
	v_cvt_pk_bf16_f32 v143, v145, v148
	global_store_dwordx4 v[146:147], v[140:143], off offset:256 nt
	v_mul_lo_u32 v137, s15, v135
	v_pk_mul_f32 v[146:147], v[74:75], v[138:139] op_sel_hi:[1,0]
	v_mad_u64_u32 v[140:141], s[2:3], s14, v135, 0
	v_add3_u32 v141, v141, v131, v137
	v_lshl_add_u64 v[144:145], v[140:141], 1, v[132:133]
	v_pk_mul_f32 v[140:141], v[78:79], v[138:139] op_sel_hi:[1,0]
	v_pk_mul_f32 v[142:143], v[76:77], v[138:139] op_sel_hi:[1,0]
	v_max_f32_e32 v140, 0, v140
	v_pk_mul_f32 v[148:149], v[72:73], v[138:139] op_sel_hi:[1,0]
	v_max_f32_e32 v131, 0, v142
	v_max_f32_e32 v137, 0, v143
	v_max_f32_e32 v142, 0, v146
	v_mul_f32_e32 v143, v140, v140
	v_max_f32_e32 v140, 0, v141
	v_max_f32_e32 v135, 0, v148
	v_max_f32_e32 v139, 0, v149
	v_mul_f32_e32 v146, v142, v142
	v_max_f32_e32 v141, 0, v147
	v_mul_f32_e32 v142, v140, v140
	v_mul_f32_e32 v131, v131, v131
	v_mul_f32_e32 v135, v135, v135
	v_mul_f32_e32 v137, v137, v137
	v_mul_f32_e32 v139, v139, v139
	v_mul_f32_e32 v147, v141, v141
	v_cvt_pk_bf16_f32 v140, v131, v137
	v_cvt_pk_bf16_f32 v141, v143, v142
	v_cvt_pk_bf16_f32 v142, v135, v139
	v_cvt_pk_bf16_f32 v143, v146, v147
	global_store_dwordx4 v[144:145], v[140:143], off nt
	v_pk_mul_f32 v[146:147], v[66:67], v[138:139] op_sel_hi:[1,0]
	s_nop 0
	v_pk_mul_f32 v[140:141], v[70:71], v[138:139] op_sel_hi:[1,0]
	v_pk_mul_f32 v[142:143], v[68:69], v[138:139] op_sel_hi:[1,0]
	v_pk_mul_f32 v[138:139], v[64:65], v[138:139] op_sel_hi:[1,0]
	v_max_f32_e32 v131, 0, v142
	v_max_f32_e32 v135, 0, v138
	v_max_f32_e32 v138, 0, v139
	v_mul_f32_e32 v142, v138, v138
	v_max_f32_e32 v138, 0, v140
	v_mul_f32_e32 v131, v131, v131
	v_max_f32_e32 v137, 0, v143
	v_max_f32_e32 v139, 0, v146
	v_mul_f32_e32 v140, v138, v138
	v_max_f32_e32 v138, 0, v141
	v_mul_f32_e32 v135, v135, v135
	v_mul_f32_e32 v137, v137, v137
	v_mul_f32_e32 v143, v139, v139
	v_max_f32_e32 v139, 0, v147
	v_mul_f32_e32 v141, v138, v138
	v_cvt_pk_bf16_f32 v138, v131, v137
	v_add_u32_e32 v131, 0x80, v129
	v_mul_f32_e32 v146, v139, v139
	v_cvt_pk_bf16_f32 v139, v140, v141
	v_cvt_pk_bf16_f32 v140, v135, v142
	v_ashrrev_i32_e32 v135, 31, v131
	v_cvt_pk_bf16_f32 v141, v143, v146
	global_store_dwordx4 v[144:145], v[138:141], off offset:256 nt
	v_mul_lo_u32 v135, s14, v135
	v_mul_lo_u32 v137, s15, v131
	v_mad_u64_u32 v[138:139], s[2:3], s14, v131, 0
	v_add3_u32 v139, v139, v135, v137
	v_lshl_add_u64 v[142:143], v[138:139], 1, v[132:133]
	v_pk_mul_f32 v[138:139], v[62:63], v[136:137] op_sel_hi:[1,0]
	v_pk_mul_f32 v[140:141], v[60:61], v[136:137] op_sel_hi:[1,0]
	v_pk_mul_f32 v[144:145], v[58:59], v[136:137] op_sel_hi:[1,0]
	v_pk_mul_f32 v[146:147], v[56:57], v[136:137] op_sel_hi:[1,0]
	v_max_f32_e32 v131, 0, v140
	v_max_f32_e32 v137, 0, v141
	v_max_f32_e32 v140, 0, v147
	v_max_f32_e32 v138, 0, v138
	v_max_f32_e32 v141, 0, v144
	v_max_f32_e32 v135, 0, v146
	v_mul_f32_e32 v140, v140, v140
	v_mul_f32_e32 v144, v138, v138
	v_mul_f32_e32 v141, v141, v141
	v_max_f32_e32 v138, 0, v139
	v_max_f32_e32 v139, 0, v145
	v_mul_f32_e32 v131, v131, v131
	v_mul_f32_e32 v135, v135, v135
	v_mul_f32_e32 v137, v137, v137
	v_mul_f32_e32 v145, v138, v138
	v_mul_f32_e32 v146, v139, v139
	v_cvt_pk_bf16_f32 v138, v131, v137
	v_cvt_pk_bf16_f32 v139, v144, v145
	v_cvt_pk_bf16_f32 v140, v135, v140
	v_cvt_pk_bf16_f32 v141, v141, v146
	global_store_dwordx4 v[142:143], v[138:141], off nt
	v_pk_mul_f32 v[144:145], v[50:51], v[136:137] op_sel_hi:[1,0]
	s_nop 0
	v_pk_mul_f32 v[138:139], v[54:55], v[136:137] op_sel_hi:[1,0]
	v_pk_mul_f32 v[140:141], v[52:53], v[136:137] op_sel_hi:[1,0]
	v_pk_mul_f32 v[136:137], v[48:49], v[136:137] op_sel_hi:[1,0]
	v_max_f32_e32 v131, 0, v140
	v_max_f32_e32 v137, 0, v137
	v_max_f32_e32 v135, 0, v136
	v_max_f32_e32 v136, 0, v141
	v_mul_f32_e32 v140, v137, v137
	v_max_f32_e32 v137, 0, v138
	v_max_f32_e32 v138, 0, v144
	v_mul_f32_e32 v131, v131, v131
	v_mul_f32_e32 v136, v136, v136
	v_mul_f32_e32 v141, v138, v138
	v_max_f32_e32 v138, 0, v139
	v_mul_f32_e32 v135, v135, v135
	v_mul_f32_e32 v137, v137, v137
	v_max_f32_e32 v139, 0, v145
	v_mul_f32_e32 v138, v138, v138
	v_cvt_pk_bf16_f32 v136, v131, v136
	v_add_u32_e32 v131, 0x90, v129
	v_mul_f32_e32 v139, v139, v139
	v_cvt_pk_bf16_f32 v137, v137, v138
	v_cvt_pk_bf16_f32 v138, v135, v140
	v_ashrrev_i32_e32 v135, 31, v131
	v_cvt_pk_bf16_f32 v139, v141, v139
	global_store_dwordx4 v[142:143], v[136:139], off offset:256 nt
	v_mul_lo_u32 v135, s14, v135
	v_pk_mul_f32 v[144:145], v[40:41], v[134:135] op_sel_hi:[1,0]
	v_mul_lo_u32 v138, s15, v131
	v_mad_u64_u32 v[136:137], s[2:3], s14, v131, 0
	v_add3_u32 v137, v137, v135, v138
	v_lshl_add_u64 v[140:141], v[136:137], 1, v[132:133]
	v_pk_mul_f32 v[136:137], v[46:47], v[134:135] op_sel_hi:[1,0]
	v_pk_mul_f32 v[138:139], v[44:45], v[134:135] op_sel_hi:[1,0]
	v_pk_mul_f32 v[142:143], v[42:43], v[134:135] op_sel_hi:[1,0]
	v_max_f32_e32 v131, 0, v138
	v_max_f32_e32 v138, 0, v139
	v_max_f32_e32 v139, 0, v145
	v_max_f32_e32 v136, 0, v136
	v_max_f32_e32 v135, 0, v144
	v_mul_f32_e32 v138, v138, v138
	v_mul_f32_e32 v139, v139, v139
	v_max_f32_e32 v142, 0, v142
	v_mul_f32_e32 v144, v136, v136
	v_max_f32_e32 v136, 0, v137
	v_max_f32_e32 v137, 0, v143
	v_mul_f32_e32 v131, v131, v131
	v_mul_f32_e32 v135, v135, v135
	v_mul_f32_e32 v142, v142, v142
	v_mul_f32_e32 v143, v136, v136
	v_mul_f32_e32 v145, v137, v137
	v_cvt_pk_bf16_f32 v136, v131, v138
	v_cvt_pk_bf16_f32 v137, v144, v143
	v_cvt_pk_bf16_f32 v138, v135, v139
	v_cvt_pk_bf16_f32 v139, v142, v145
	global_store_dwordx4 v[140:141], v[136:139], off nt
	v_pk_mul_f32 v[142:143], v[34:35], v[134:135] op_sel_hi:[1,0]
	s_nop 0
	v_pk_mul_f32 v[136:137], v[38:39], v[134:135] op_sel_hi:[1,0]
	v_pk_mul_f32 v[138:139], v[36:37], v[134:135] op_sel_hi:[1,0]
	v_pk_mul_f32 v[134:135], v[32:33], v[134:135] op_sel_hi:[1,0]
	v_max_f32_e32 v131, 0, v138
	v_max_f32_e32 v134, 0, v134
	v_max_f32_e32 v135, 0, v135
	v_mul_f32_e32 v138, v134, v134
	v_max_f32_e32 v134, 0, v139
	v_mul_f32_e32 v139, v135, v135
	v_max_f32_e32 v135, 0, v136
	v_max_f32_e32 v136, 0, v142
	v_mul_f32_e32 v131, v131, v131
	v_mul_f32_e32 v134, v134, v134
	v_mul_f32_e32 v142, v136, v136
	v_max_f32_e32 v136, 0, v137
	v_max_f32_e32 v137, 0, v143
	v_mul_f32_e32 v135, v135, v135
	v_mul_f32_e32 v136, v136, v136
	v_mul_f32_e32 v137, v137, v137
	v_cvt_pk_bf16_f32 v134, v131, v134
	v_add_u32_e32 v131, 0xa0, v129
	v_cvt_pk_bf16_f32 v135, v135, v136
	v_cvt_pk_bf16_f32 v136, v138, v139
	v_cvt_pk_bf16_f32 v137, v142, v137
	global_store_dwordx4 v[140:141], v[134:137], off offset:256 nt
	v_pk_mul_f32 v[142:143], v[24:25], v[130:131] op_sel_hi:[1,0]
	v_pk_mul_f32 v[140:141], v[26:27], v[130:131] op_sel_hi:[1,0]
	v_ashrrev_i32_e32 v134, 31, v131
	v_mul_lo_u32 v136, s14, v134
	v_mul_lo_u32 v137, s15, v131
	v_mad_u64_u32 v[134:135], s[2:3], s14, v131, 0
	v_add3_u32 v135, v135, v136, v137
	v_lshl_add_u64 v[138:139], v[134:135], 1, v[132:133]
	v_pk_mul_f32 v[134:135], v[30:31], v[130:131] op_sel_hi:[1,0]
	v_pk_mul_f32 v[136:137], v[28:29], v[130:131] op_sel_hi:[1,0]
	v_max_f32_e32 v134, 0, v134
	v_max_f32_e32 v131, 0, v136
	v_max_f32_e32 v136, 0, v142
	v_max_f32_e32 v137, 0, v137
	v_mul_f32_e32 v136, v136, v136
	v_max_f32_e32 v142, 0, v143
	v_mul_f32_e32 v137, v137, v137
	v_max_f32_e32 v140, 0, v140
	v_mul_f32_e32 v143, v134, v134
	v_max_f32_e32 v134, 0, v135
	v_max_f32_e32 v135, 0, v141
	v_mul_f32_e32 v131, v131, v131
	v_mul_f32_e32 v142, v142, v142
	v_mul_f32_e32 v140, v140, v140
	v_mul_f32_e32 v141, v134, v134
	v_mul_f32_e32 v144, v135, v135
	v_cvt_pk_bf16_f32 v134, v131, v137
	v_cvt_pk_bf16_f32 v135, v143, v141
	v_cvt_pk_bf16_f32 v136, v136, v142
	v_cvt_pk_bf16_f32 v137, v140, v144
	global_store_dwordx4 v[138:139], v[134:137], off nt
	v_pk_mul_f32 v[140:141], v[18:19], v[130:131] op_sel_hi:[1,0]
	v_add_u32_e32 v129, 0xb0, v129
	v_pk_mul_f32 v[134:135], v[22:23], v[130:131] op_sel_hi:[1,0]
	v_pk_mul_f32 v[136:137], v[20:21], v[130:131] op_sel_hi:[1,0]
	v_pk_mul_f32 v[130:131], v[16:17], v[130:131] op_sel_hi:[1,0]
	v_max_f32_e32 v136, 0, v136
	v_max_f32_e32 v130, 0, v130
	v_max_f32_e32 v134, 0, v134
	v_mul_f32_e32 v136, v136, v136
	v_mul_f32_e32 v130, v130, v130
	v_max_f32_e32 v137, 0, v137
	v_max_f32_e32 v131, 0, v131
	v_mul_f32_e32 v142, v134, v134
	v_max_f32_e32 v134, 0, v135
	v_max_f32_e32 v135, 0, v141
	v_mul_f32_e32 v137, v137, v137
	v_mul_f32_e32 v131, v131, v131
	v_max_f32_e32 v140, 0, v140
	v_mul_f32_e32 v141, v134, v134
	v_mul_f32_e32 v143, v135, v135
	v_cvt_pk_bf16_f32 v134, v136, v137
	v_cvt_pk_bf16_f32 v135, v142, v141
	v_cvt_pk_bf16_f32 v136, v130, v131
	v_ashrrev_i32_e32 v130, 31, v129
	v_mul_f32_e32 v140, v140, v140
	v_cvt_pk_bf16_f32 v137, v140, v143
	global_store_dwordx4 v[138:139], v[134:137], off offset:256 nt
	v_pk_mul_f32 v[138:139], v[8:9], v[128:129] op_sel_hi:[1,0]
	s_nop 0
	v_mul_lo_u32 v134, s14, v130
	v_mul_lo_u32 v135, s15, v129
	v_mad_u64_u32 v[130:131], s[2:3], s14, v129, 0
	v_add3_u32 v131, v131, v134, v135
	v_lshl_add_u64 v[134:135], v[130:131], 1, v[132:133]
	v_pk_mul_f32 v[130:131], v[14:15], v[128:129] op_sel_hi:[1,0]
	v_pk_mul_f32 v[132:133], v[12:13], v[128:129] op_sel_hi:[1,0]
	v_pk_mul_f32 v[136:137], v[10:11], v[128:129] op_sel_hi:[1,0]
	v_max_f32_e32 v129, 0, v132
	v_max_f32_e32 v132, 0, v138
	v_max_f32_e32 v133, 0, v133
	v_max_f32_e32 v130, 0, v130
	v_mul_f32_e32 v132, v132, v132
	v_max_f32_e32 v138, 0, v139
	v_mul_f32_e32 v133, v133, v133
	v_max_f32_e32 v136, 0, v136
	v_mul_f32_e32 v139, v130, v130
	v_max_f32_e32 v130, 0, v131
	v_max_f32_e32 v131, 0, v137
	v_mul_f32_e32 v129, v129, v129
	v_mul_f32_e32 v138, v138, v138
	v_mul_f32_e32 v136, v136, v136
	v_mul_f32_e32 v137, v130, v130
	v_mul_f32_e32 v140, v131, v131
	v_cvt_pk_bf16_f32 v130, v129, v133
	v_cvt_pk_bf16_f32 v131, v139, v137
	v_cvt_pk_bf16_f32 v132, v132, v138
	v_cvt_pk_bf16_f32 v133, v136, v140
	global_store_dwordx4 v[134:135], v[130:133], off nt
	v_pk_mul_f32 v[136:137], v[2:3], v[128:129] op_sel_hi:[1,0]
	s_mov_b64 s[2:3], 0
	v_pk_mul_f32 v[130:131], v[6:7], v[128:129] op_sel_hi:[1,0]
	v_pk_mul_f32 v[132:133], v[4:5], v[128:129] op_sel_hi:[1,0]
	v_pk_mul_f32 v[128:129], v[0:1], v[128:129] op_sel_hi:[1,0]
	v_max_f32_e32 v132, 0, v132
	v_max_f32_e32 v128, 0, v128
	v_max_f32_e32 v129, 0, v129
	v_mul_f32_e32 v138, v128, v128
	v_max_f32_e32 v128, 0, v133
	v_mul_f32_e32 v133, v129, v129
	v_max_f32_e32 v129, 0, v130
	v_max_f32_e32 v130, 0, v136
	v_mul_f32_e32 v136, v130, v130
	v_max_f32_e32 v130, 0, v131
	v_max_f32_e32 v131, 0, v137
	v_mul_f32_e32 v128, v128, v128
	v_mul_f32_e32 v129, v129, v129
	v_mul_f32_e32 v130, v130, v130
	v_mul_f32_e32 v131, v131, v131
	v_mul_f32_e32 v132, v132, v132
	v_cvt_pk_bf16_f32 v128, v132, v128
	v_cvt_pk_bf16_f32 v129, v129, v130
	v_cvt_pk_bf16_f32 v130, v138, v133
	v_cvt_pk_bf16_f32 v131, v136, v131
	global_store_dwordx4 v[134:135], v[128:131], off offset:256 nt
